# gate/up weight conversion fast path (3 steps of loads in flight, conflict-free LDS) on top of v83
# speedup vs baseline: 1.0188x; 1.0018x over previous
; __device__ __forceinline__ unsigned cvt_pk_bf16(float lo, float hi) { unsigned r; asm volatile("v_cvt_pk_bf16_f32 %0, %1, %2" : "=v"(r) : "v"(lo), "v"(hi)); return r; }
; __device__ __forceinline__ int perm_n0(int type, int p0, int& use1) {
;     ...
;     const int tile = p0 >> 8, q = p0 & 255; if (q < 128) return tile * 128 + q; use1 = 1; return tile * 128 + q - 128;
; __device__ __forceinline__ void transpose_w(const float* __restrict__ src0, const float* __restrict__ src1, int K, int N, bf16_t* __restrict__ dst, int P, int type, float* tl, int first, int stride) {
;   const int tid = threadIdx.x, nkt = K / 128, ntiles = nkt * (P / 64), c32 = tid & 31, kq = tid >> 5;
;   for (int t = first; t < ntiles; t += stride) {
;     const int pi = t / nkt, ki = t - pi * nkt, p0 = pi * 64, k0 = ki * 128;
;     int u0, u1; const int n0a = perm_n0(type, p0, u0), n0b = perm_n0(type, p0 + 32, u1);
;     const float* sa = (u0 ? src1 : src0) + (size_t)k0 * N + (n0a < 0 ? 0 : n0a) + c32; const float* sb = (u1 ? src1 : src0) + (size_t)k0 * N + (n0b < 0 ? 0 : n0b) + c32;
;     float va[8], vb[8];
; #pragma unroll
;     for (int i = 0; i < 8; ++i) { va[i] = sa[(size_t)(kq + 16 * i) * N]; vb[i] = sb[(size_t)(kq + 16 * i) * N]; }
;     __syncthreads();
; #pragma unroll
;     for (int i = 0; i < 8; ++i) { tl[(kq + 16 * i) * 33 + c32] = n0a < 0 ? 0.f : va[i]; tl[128 * 33 + (kq + 16 * i) * 33 + c32] = n0b < 0 ? 0.f : vb[i]; }
;     __syncthreads();
;     const int row = tid >> 4, kc = (tid & 15) * 8;
; #pragma unroll
;     for (int h = 0; h < 2; ++h) { const float* q = tl + h * 128 * 33 + kc * 33 + row;
;       u32x4 w; w.x = cvt_pk_bf16(q[0], q[33]); w.y = cvt_pk_bf16(q[66], q[99]); w.z = cvt_pk_bf16(q[132], q[165]); w.w = cvt_pk_bf16(q[198], q[231]);
;       *(u32x4*)(dst + (size_t)(p0 + h * 32 + row) * K + k0 + kc) = w; }
.LBB0_73:
	s_cmpk_eq_i32 s78, 0x100
	s_cbranch_scc0 .Lgu_orig
	v_lshrrev_b32_e32 v148, 5, v187
	v_and_b32_e32 v149, 31, v187
	s_movk_i32 s0, 0x1600
	v_add_u32_e32 v112, 0, v148
	v_mad_u32_u24 v112, v112, s0, v149
	v_lshlrev_b32_e32 v112, 2, v112
	v_add_u32_e32 v113, 16, v148
	v_mad_u32_u24 v113, v113, s0, v149
	v_lshlrev_b32_e32 v113, 2, v113
	v_add_u32_e32 v114, 32, v148
	v_mad_u32_u24 v114, v114, s0, v149
	v_lshlrev_b32_e32 v114, 2, v114
	v_add_u32_e32 v115, 48, v148
	v_mad_u32_u24 v115, v115, s0, v149
	v_lshlrev_b32_e32 v115, 2, v115
	v_add_u32_e32 v116, 64, v148
	v_mad_u32_u24 v116, v116, s0, v149
	v_lshlrev_b32_e32 v116, 2, v116
	v_add_u32_e32 v117, 80, v148
	v_mad_u32_u24 v117, v117, s0, v149
	v_lshlrev_b32_e32 v117, 2, v117
	v_add_u32_e32 v118, 96, v148
	v_mad_u32_u24 v118, v118, s0, v149
	v_lshlrev_b32_e32 v118, 2, v118
	v_add_u32_e32 v119, 112, v148
	v_mad_u32_u24 v119, v119, s0, v149
	v_lshlrev_b32_e32 v119, 2, v119
	v_mad_u32_u24 v120, v148, 33, v149
	v_lshlrev_b32_e32 v120, 2, v120
	v_lshrrev_b32_e32 v149, 3, v187
	v_and_b32_e32 v149, 12, v149
	v_and_b32_e32 v148, 3, v187
	v_or_b32_e32 v149, v149, v148
	v_lshlrev_b32_e32 v149, 3, v149
	v_lshrrev_b32_e32 v148, 4, v187
	v_and_b32_e32 v148, 24, v148
	v_bfe_u32 v121, v187, 2, 3
	v_or_b32_e32 v148, v148, v121
	v_mad_u32_u24 v121, v149, 33, v148
	v_lshlrev_b32_e32 v121, 2, v121
	v_add_u32_e32 v122, 0x4200, v121
	v_lshl_add_u32 v123, v148, 11, v149
	v_lshlrev_b32_e32 v123, 1, v123
	s_lshr_b32 s0, s14, 4
	s_and_b32 s1, s14, 15
	s_lshl_b32 s1, s1, 7
	s_and_b32 s4, s0, 2
	s_cmp_lg_u32 s4, 0
	s_cselect_b32 s20, s30, s28
	s_cselect_b32 s21, s31, s29
	s_and_b32 s4, s0, 1
	s_lshl_b32 s4, s4, 6
	s_lshr_b32 s5, s14, 6
	s_lshl_b32 s5, s5, 7
	s_add_u32 s4, s4, s5
	s_mul_i32 s5, s1, 0x1600
	s_add_u32 s4, s4, s5
	s_lshl_b32 s4, s4, 2
	s_add_u32 s20, s20, s4
	s_addc_u32 s21, s21, 0
	s_lshl_b32 s4, s0, 17
	s_add_u32 s4, s4, s1
	s_lshl_b32 s4, s4, 1
	s_add_u32 s22, s74, 0x2280000
	s_addc_u32 s23, s75, 0
	s_add_u32 s22, s22, s4
	s_addc_u32 s23, s23, 0
	global_load_dword v64, v112, s[20:21]
	global_load_dword v72, v112, s[20:21] offset:128
	global_load_dword v65, v113, s[20:21]
	global_load_dword v73, v113, s[20:21] offset:128
	global_load_dword v66, v114, s[20:21]
	global_load_dword v74, v114, s[20:21] offset:128
	global_load_dword v67, v115, s[20:21]
	global_load_dword v75, v115, s[20:21] offset:128
	global_load_dword v68, v116, s[20:21]
	global_load_dword v76, v116, s[20:21] offset:128
	global_load_dword v69, v117, s[20:21]
	global_load_dword v77, v117, s[20:21] offset:128
	global_load_dword v70, v118, s[20:21]
	global_load_dword v78, v118, s[20:21] offset:128
	global_load_dword v71, v119, s[20:21]
	global_load_dword v79, v119, s[20:21] offset:128
	s_add_u32 s20, s20, 0x800
	s_addc_u32 s21, s21, 0
	global_load_dword v80, v112, s[20:21]
	global_load_dword v88, v112, s[20:21] offset:128
	global_load_dword v81, v113, s[20:21]
	global_load_dword v89, v113, s[20:21] offset:128
	global_load_dword v82, v114, s[20:21]
	global_load_dword v90, v114, s[20:21] offset:128
	global_load_dword v83, v115, s[20:21]
	global_load_dword v91, v115, s[20:21] offset:128
	global_load_dword v84, v116, s[20:21]
	global_load_dword v92, v116, s[20:21] offset:128
	global_load_dword v85, v117, s[20:21]
	global_load_dword v93, v117, s[20:21] offset:128
	global_load_dword v86, v118, s[20:21]
	global_load_dword v94, v118, s[20:21] offset:128
	global_load_dword v87, v119, s[20:21]
	global_load_dword v95, v119, s[20:21] offset:128
	s_add_u32 s20, s20, 0x800
	s_addc_u32 s21, s21, 0
	global_load_dword v96, v112, s[20:21]
	global_load_dword v104, v112, s[20:21] offset:128
	global_load_dword v97, v113, s[20:21]
	global_load_dword v105, v113, s[20:21] offset:128
	global_load_dword v98, v114, s[20:21]
	global_load_dword v106, v114, s[20:21] offset:128
	global_load_dword v99, v115, s[20:21]
	global_load_dword v107, v115, s[20:21] offset:128
	global_load_dword v100, v116, s[20:21]
	global_load_dword v108, v116, s[20:21] offset:128
	global_load_dword v101, v117, s[20:21]
	global_load_dword v109, v117, s[20:21] offset:128
	global_load_dword v102, v118, s[20:21]
	global_load_dword v110, v118, s[20:21] offset:128
	global_load_dword v103, v119, s[20:21]
	global_load_dword v111, v119, s[20:21] offset:128
	s_add_u32 s20, s20, 0x800
	s_addc_u32 s21, s21, 0
	s_barrier
	s_waitcnt vmcnt(32)
	ds_write_b32 v120, v64 offset:0
	ds_write_b32 v120, v72 offset:16896
	ds_write_b32 v120, v65 offset:2112
	ds_write_b32 v120, v73 offset:19008
	ds_write_b32 v120, v66 offset:4224
	ds_write_b32 v120, v74 offset:21120
	ds_write_b32 v120, v67 offset:6336
	ds_write_b32 v120, v75 offset:23232
	ds_write_b32 v120, v68 offset:8448
	ds_write_b32 v120, v76 offset:25344
	ds_write_b32 v120, v69 offset:10560
	ds_write_b32 v120, v77 offset:27456
	ds_write_b32 v120, v70 offset:12672
	ds_write_b32 v120, v78 offset:29568
	ds_write_b32 v120, v71 offset:14784
	ds_write_b32 v120, v79 offset:31680
	s_waitcnt lgkmcnt(0)
	s_barrier
; __device__ __forceinline__ unsigned cvt_pk_bf16(float lo, float hi) { unsigned r; asm volatile("v_cvt_pk_bf16_f32 %0, %1, %2" : "=v"(r) : "v"(lo), "v"(hi)); return r; }
; __device__ __forceinline__ void transpose_w(const float* __restrict__ src0, const float* __restrict__ src1, int K, int N, bf16_t* __restrict__ dst, int P, int type, float* tl, int first, int stride) {
;     ...
;   for (int t = first; t < ntiles; t += stride) {
;     const int pi = t / nkt, ki = t - pi * nkt, p0 = pi * 64, k0 = ki * 128;
;     int u0, u1; const int n0a = perm_n0(type, p0, u0), n0b = perm_n0(type, p0 + 32, u1);
;     const float* sa = (u0 ? src1 : src0) + (size_t)k0 * N + (n0a < 0 ? 0 : n0a) + c32; const float* sb = (u1 ? src1 : src0) + (size_t)k0 * N + (n0b < 0 ? 0 : n0b) + c32;
;     float va[8], vb[8];
; #pragma unroll
;     for (int i = 0; i < 8; ++i) { va[i] = sa[(size_t)(kq + 16 * i) * N]; vb[i] = sb[(size_t)(kq + 16 * i) * N]; }
;     __syncthreads();
; #pragma unroll
;     for (int i = 0; i < 8; ++i) { tl[(kq + 16 * i) * 33 + c32] = n0a < 0 ? 0.f : va[i]; tl[128 * 33 + (kq + 16 * i) * 33 + c32] = n0b < 0 ? 0.f : vb[i]; }
;     __syncthreads();
;     const int row = tid >> 4, kc = (tid & 15) * 8;
; #pragma unroll
;     for (int h = 0; h < 2; ++h) { const float* q = tl + h * 128 * 33 + kc * 33 + row;
;       u32x4 w; w.x = cvt_pk_bf16(q[0], q[33]); w.y = cvt_pk_bf16(q[66], q[99]); w.z = cvt_pk_bf16(q[132], q[165]); w.w = cvt_pk_bf16(q[198], q[231]);
;       *(u32x4*)(dst + (size_t)(p0 + h * 32 + row) * K + k0 + kc) = w; }
	ds_read_b32 v124, v121 offset:0
	ds_read_b32 v125, v121 offset:132
	ds_read_b32 v126, v121 offset:264
	ds_read_b32 v127, v121 offset:396
	ds_read_b32 v128, v121 offset:528
	ds_read_b32 v129, v121 offset:660
	ds_read_b32 v130, v121 offset:792
	ds_read_b32 v131, v121 offset:924
	ds_read_b32 v132, v122 offset:0
	ds_read_b32 v133, v122 offset:132
	ds_read_b32 v134, v122 offset:264
	ds_read_b32 v135, v122 offset:396
	ds_read_b32 v136, v122 offset:528
	ds_read_b32 v137, v122 offset:660
	ds_read_b32 v138, v122 offset:792
	ds_read_b32 v139, v122 offset:924
	s_waitcnt lgkmcnt(8)
	v_cvt_pk_bf16_f32 v140, v124, v125
	v_cvt_pk_bf16_f32 v141, v126, v127
	v_cvt_pk_bf16_f32 v142, v128, v129
	v_cvt_pk_bf16_f32 v143, v130, v131
	global_store_dwordx4 v123, v[140:143], s[22:23]
	s_waitcnt lgkmcnt(0)
	v_cvt_pk_bf16_f32 v144, v132, v133
	v_cvt_pk_bf16_f32 v145, v134, v135
	v_cvt_pk_bf16_f32 v146, v136, v137
	v_cvt_pk_bf16_f32 v147, v138, v139
	s_add_u32 s4, s22, 0x20000
	s_addc_u32 s5, s23, 0
	global_store_dwordx4 v123, v[144:147], s[4:5]
	s_add_u32 s22, s22, 0x400000
	s_addc_u32 s23, s23, 0
	global_load_dword v64, v112, s[20:21]
	global_load_dword v72, v112, s[20:21] offset:128
	global_load_dword v65, v113, s[20:21]
	global_load_dword v73, v113, s[20:21] offset:128
	global_load_dword v66, v114, s[20:21]
	global_load_dword v74, v114, s[20:21] offset:128
	global_load_dword v67, v115, s[20:21]
	global_load_dword v75, v115, s[20:21] offset:128
	global_load_dword v68, v116, s[20:21]
	global_load_dword v76, v116, s[20:21] offset:128
	global_load_dword v69, v117, s[20:21]
	global_load_dword v77, v117, s[20:21] offset:128
	global_load_dword v70, v118, s[20:21]
	global_load_dword v78, v118, s[20:21] offset:128
	global_load_dword v71, v119, s[20:21]
	global_load_dword v79, v119, s[20:21] offset:128
	s_add_u32 s20, s20, 0x800
	s_addc_u32 s21, s21, 0
	s_waitcnt vmcnt(34)
	ds_write_b32 v120, v80 offset:33792
	ds_write_b32 v120, v88 offset:50688
	ds_write_b32 v120, v81 offset:35904
	ds_write_b32 v120, v89 offset:52800
	ds_write_b32 v120, v82 offset:38016
	ds_write_b32 v120, v90 offset:54912
	ds_write_b32 v120, v83 offset:40128
	ds_write_b32 v120, v91 offset:57024
	ds_write_b32 v120, v84 offset:42240
	ds_write_b32 v120, v92 offset:59136
	ds_write_b32 v120, v85 offset:44352
	ds_write_b32 v120, v93 offset:61248
	ds_write_b32 v120, v86 offset:46464
	ds_write_b32 v120, v94 offset:63360
	ds_write_b32 v120, v87 offset:48576
	ds_write_b32 v120, v95 offset:65472
	s_waitcnt lgkmcnt(0)
	s_barrier
	ds_read_b32 v124, v121 offset:33792
	ds_read_b32 v125, v121 offset:33924
	ds_read_b32 v126, v121 offset:34056
	ds_read_b32 v127, v121 offset:34188
	ds_read_b32 v128, v121 offset:34320
	ds_read_b32 v129, v121 offset:34452
	ds_read_b32 v130, v121 offset:34584
	ds_read_b32 v131, v121 offset:34716
	ds_read_b32 v132, v122 offset:33792
	ds_read_b32 v133, v122 offset:33924
	ds_read_b32 v134, v122 offset:34056
	ds_read_b32 v135, v122 offset:34188
	ds_read_b32 v136, v122 offset:34320
	ds_read_b32 v137, v122 offset:34452
	ds_read_b32 v138, v122 offset:34584
	ds_read_b32 v139, v122 offset:34716
	s_waitcnt lgkmcnt(8)
	v_cvt_pk_bf16_f32 v140, v124, v125
	v_cvt_pk_bf16_f32 v141, v126, v127
	v_cvt_pk_bf16_f32 v142, v128, v129
	v_cvt_pk_bf16_f32 v143, v130, v131
	global_store_dwordx4 v123, v[140:143], s[22:23]
	s_waitcnt lgkmcnt(0)
	v_cvt_pk_bf16_f32 v144, v132, v133
	v_cvt_pk_bf16_f32 v145, v134, v135
	v_cvt_pk_bf16_f32 v146, v136, v137
	v_cvt_pk_bf16_f32 v147, v138, v139
	s_add_u32 s4, s22, 0x20000
	s_addc_u32 s5, s23, 0
	global_store_dwordx4 v123, v[144:147], s[4:5]
	s_add_u32 s22, s22, 0x400000
	s_addc_u32 s23, s23, 0
	global_load_dword v80, v112, s[20:21]
	global_load_dword v88, v112, s[20:21] offset:128
	global_load_dword v81, v113, s[20:21]
	global_load_dword v89, v113, s[20:21] offset:128
	global_load_dword v82, v114, s[20:21]
	global_load_dword v90, v114, s[20:21] offset:128
	global_load_dword v83, v115, s[20:21]
	global_load_dword v91, v115, s[20:21] offset:128
	global_load_dword v84, v116, s[20:21]
	global_load_dword v92, v116, s[20:21] offset:128
	global_load_dword v85, v117, s[20:21]
	global_load_dword v93, v117, s[20:21] offset:128
	global_load_dword v86, v118, s[20:21]
	global_load_dword v94, v118, s[20:21] offset:128
	global_load_dword v87, v119, s[20:21]
	global_load_dword v95, v119, s[20:21] offset:128
	s_add_u32 s20, s20, 0x800
	s_addc_u32 s21, s21, 0
	s_waitcnt vmcnt(36)
	ds_write_b32 v120, v96 offset:0
	ds_write_b32 v120, v104 offset:16896
	ds_write_b32 v120, v97 offset:2112
	ds_write_b32 v120, v105 offset:19008
	ds_write_b32 v120, v98 offset:4224
	ds_write_b32 v120, v106 offset:21120
	ds_write_b32 v120, v99 offset:6336
	ds_write_b32 v120, v107 offset:23232
	ds_write_b32 v120, v100 offset:8448
	ds_write_b32 v120, v108 offset:25344
	ds_write_b32 v120, v101 offset:10560
	ds_write_b32 v120, v109 offset:27456
	ds_write_b32 v120, v102 offset:12672
	ds_write_b32 v120, v110 offset:29568
	ds_write_b32 v120, v103 offset:14784
	ds_write_b32 v120, v111 offset:31680
	s_waitcnt lgkmcnt(0)
	s_barrier
; __device__ __forceinline__ unsigned cvt_pk_bf16(float lo, float hi) { unsigned r; asm volatile("v_cvt_pk_bf16_f32 %0, %1, %2" : "=v"(r) : "v"(lo), "v"(hi)); return r; }
; __device__ __forceinline__ void transpose_w(const float* __restrict__ src0, const float* __restrict__ src1, int K, int N, bf16_t* __restrict__ dst, int P, int type, float* tl, int first, int stride) {
;     ...
;   for (int t = first; t < ntiles; t += stride) {
;     const int pi = t / nkt, ki = t - pi * nkt, p0 = pi * 64, k0 = ki * 128;
;     int u0, u1; const int n0a = perm_n0(type, p0, u0), n0b = perm_n0(type, p0 + 32, u1);
;     const float* sa = (u0 ? src1 : src0) + (size_t)k0 * N + (n0a < 0 ? 0 : n0a) + c32; const float* sb = (u1 ? src1 : src0) + (size_t)k0 * N + (n0b < 0 ? 0 : n0b) + c32;
;     float va[8], vb[8];
; #pragma unroll
;     for (int i = 0; i < 8; ++i) { va[i] = sa[(size_t)(kq + 16 * i) * N]; vb[i] = sb[(size_t)(kq + 16 * i) * N]; }
;     __syncthreads();
; #pragma unroll
;     for (int i = 0; i < 8; ++i) { tl[(kq + 16 * i) * 33 + c32] = n0a < 0 ? 0.f : va[i]; tl[128 * 33 + (kq + 16 * i) * 33 + c32] = n0b < 0 ? 0.f : vb[i]; }
;     __syncthreads();
;     const int row = tid >> 4, kc = (tid & 15) * 8;
; #pragma unroll
;     for (int h = 0; h < 2; ++h) { const float* q = tl + h * 128 * 33 + kc * 33 + row;
;       u32x4 w; w.x = cvt_pk_bf16(q[0], q[33]); w.y = cvt_pk_bf16(q[66], q[99]); w.z = cvt_pk_bf16(q[132], q[165]); w.w = cvt_pk_bf16(q[198], q[231]);
;       *(u32x4*)(dst + (size_t)(p0 + h * 32 + row) * K + k0 + kc) = w; }
	ds_read_b32 v124, v121 offset:0
	ds_read_b32 v125, v121 offset:132
	ds_read_b32 v126, v121 offset:264
	ds_read_b32 v127, v121 offset:396
	ds_read_b32 v128, v121 offset:528
	ds_read_b32 v129, v121 offset:660
	ds_read_b32 v130, v121 offset:792
	ds_read_b32 v131, v121 offset:924
	ds_read_b32 v132, v122 offset:0
	ds_read_b32 v133, v122 offset:132
	ds_read_b32 v134, v122 offset:264
	ds_read_b32 v135, v122 offset:396
	ds_read_b32 v136, v122 offset:528
	ds_read_b32 v137, v122 offset:660
	ds_read_b32 v138, v122 offset:792
	ds_read_b32 v139, v122 offset:924
	s_waitcnt lgkmcnt(8)
	v_cvt_pk_bf16_f32 v140, v124, v125
	v_cvt_pk_bf16_f32 v141, v126, v127
	v_cvt_pk_bf16_f32 v142, v128, v129
	v_cvt_pk_bf16_f32 v143, v130, v131
	global_store_dwordx4 v123, v[140:143], s[22:23]
	s_waitcnt lgkmcnt(0)
	v_cvt_pk_bf16_f32 v144, v132, v133
	v_cvt_pk_bf16_f32 v145, v134, v135
	v_cvt_pk_bf16_f32 v146, v136, v137
	v_cvt_pk_bf16_f32 v147, v138, v139
	s_add_u32 s4, s22, 0x20000
	s_addc_u32 s5, s23, 0
	global_store_dwordx4 v123, v[144:147], s[4:5]
	s_add_u32 s22, s22, 0x400000
	s_addc_u32 s23, s23, 0
	global_load_dword v96, v112, s[20:21]
	global_load_dword v104, v112, s[20:21] offset:128
	global_load_dword v97, v113, s[20:21]
	global_load_dword v105, v113, s[20:21] offset:128
	global_load_dword v98, v114, s[20:21]
	global_load_dword v106, v114, s[20:21] offset:128
	global_load_dword v99, v115, s[20:21]
	global_load_dword v107, v115, s[20:21] offset:128
	global_load_dword v100, v116, s[20:21]
	global_load_dword v108, v116, s[20:21] offset:128
	global_load_dword v101, v117, s[20:21]
	global_load_dword v109, v117, s[20:21] offset:128
	global_load_dword v102, v118, s[20:21]
	global_load_dword v110, v118, s[20:21] offset:128
	global_load_dword v103, v119, s[20:21]
	global_load_dword v111, v119, s[20:21] offset:128
	s_add_u32 s20, s20, 0x800
	s_addc_u32 s21, s21, 0
	s_waitcnt vmcnt(36)
	ds_write_b32 v120, v64 offset:33792
	ds_write_b32 v120, v72 offset:50688
	ds_write_b32 v120, v65 offset:35904
	ds_write_b32 v120, v73 offset:52800
	ds_write_b32 v120, v66 offset:38016
	ds_write_b32 v120, v74 offset:54912
	ds_write_b32 v120, v67 offset:40128
	ds_write_b32 v120, v75 offset:57024
	ds_write_b32 v120, v68 offset:42240
	ds_write_b32 v120, v76 offset:59136
	ds_write_b32 v120, v69 offset:44352
	ds_write_b32 v120, v77 offset:61248
	ds_write_b32 v120, v70 offset:46464
	ds_write_b32 v120, v78 offset:63360
	ds_write_b32 v120, v71 offset:48576
	ds_write_b32 v120, v79 offset:65472
	s_waitcnt lgkmcnt(0)
	s_barrier
	ds_read_b32 v124, v121 offset:33792
	ds_read_b32 v125, v121 offset:33924
	ds_read_b32 v126, v121 offset:34056
	ds_read_b32 v127, v121 offset:34188
	ds_read_b32 v128, v121 offset:34320
	ds_read_b32 v129, v121 offset:34452
	ds_read_b32 v130, v121 offset:34584
	ds_read_b32 v131, v121 offset:34716
	ds_read_b32 v132, v122 offset:33792
	ds_read_b32 v133, v122 offset:33924
	ds_read_b32 v134, v122 offset:34056
	ds_read_b32 v135, v122 offset:34188
	ds_read_b32 v136, v122 offset:34320
	ds_read_b32 v137, v122 offset:34452
	ds_read_b32 v138, v122 offset:34584
	ds_read_b32 v139, v122 offset:34716
	s_waitcnt lgkmcnt(8)
	v_cvt_pk_bf16_f32 v140, v124, v125
	v_cvt_pk_bf16_f32 v141, v126, v127
	v_cvt_pk_bf16_f32 v142, v128, v129
	v_cvt_pk_bf16_f32 v143, v130, v131
	global_store_dwordx4 v123, v[140:143], s[22:23]
	s_waitcnt lgkmcnt(0)
	v_cvt_pk_bf16_f32 v144, v132, v133
	v_cvt_pk_bf16_f32 v145, v134, v135
	v_cvt_pk_bf16_f32 v146, v136, v137
	v_cvt_pk_bf16_f32 v147, v138, v139
	s_add_u32 s4, s22, 0x20000
	s_addc_u32 s5, s23, 0
	global_store_dwordx4 v123, v[144:147], s[4:5]
	s_add_u32 s22, s22, 0x400000
	s_addc_u32 s23, s23, 0
	global_load_dword v64, v112, s[20:21]
	global_load_dword v72, v112, s[20:21] offset:128
	global_load_dword v65, v113, s[20:21]
	global_load_dword v73, v113, s[20:21] offset:128
	global_load_dword v66, v114, s[20:21]
	global_load_dword v74, v114, s[20:21] offset:128
	global_load_dword v67, v115, s[20:21]
	global_load_dword v75, v115, s[20:21] offset:128
	global_load_dword v68, v116, s[20:21]
	global_load_dword v76, v116, s[20:21] offset:128
	global_load_dword v69, v117, s[20:21]
	global_load_dword v77, v117, s[20:21] offset:128
	global_load_dword v70, v118, s[20:21]
	global_load_dword v78, v118, s[20:21] offset:128
	global_load_dword v71, v119, s[20:21]
	global_load_dword v79, v119, s[20:21] offset:128
	s_add_u32 s20, s20, 0x800
	s_addc_u32 s21, s21, 0
	s_waitcnt vmcnt(36)
	ds_write_b32 v120, v80 offset:0
	ds_write_b32 v120, v88 offset:16896
	ds_write_b32 v120, v81 offset:2112
	ds_write_b32 v120, v89 offset:19008
	ds_write_b32 v120, v82 offset:4224
	ds_write_b32 v120, v90 offset:21120
	ds_write_b32 v120, v83 offset:6336
	ds_write_b32 v120, v91 offset:23232
	ds_write_b32 v120, v84 offset:8448
	ds_write_b32 v120, v92 offset:25344
	ds_write_b32 v120, v85 offset:10560
	ds_write_b32 v120, v93 offset:27456
	ds_write_b32 v120, v86 offset:12672
	ds_write_b32 v120, v94 offset:29568
	ds_write_b32 v120, v87 offset:14784
	ds_write_b32 v120, v95 offset:31680
	s_waitcnt lgkmcnt(0)
	s_barrier
; __device__ __forceinline__ unsigned cvt_pk_bf16(float lo, float hi) { unsigned r; asm volatile("v_cvt_pk_bf16_f32 %0, %1, %2" : "=v"(r) : "v"(lo), "v"(hi)); return r; }
; __device__ __forceinline__ void transpose_w(const float* __restrict__ src0, const float* __restrict__ src1, int K, int N, bf16_t* __restrict__ dst, int P, int type, float* tl, int first, int stride) {
;     ...
;   for (int t = first; t < ntiles; t += stride) {
;     const int pi = t / nkt, ki = t - pi * nkt, p0 = pi * 64, k0 = ki * 128;
;     int u0, u1; const int n0a = perm_n0(type, p0, u0), n0b = perm_n0(type, p0 + 32, u1);
;     const float* sa = (u0 ? src1 : src0) + (size_t)k0 * N + (n0a < 0 ? 0 : n0a) + c32; const float* sb = (u1 ? src1 : src0) + (size_t)k0 * N + (n0b < 0 ? 0 : n0b) + c32;
;     float va[8], vb[8];
; #pragma unroll
;     for (int i = 0; i < 8; ++i) { va[i] = sa[(size_t)(kq + 16 * i) * N]; vb[i] = sb[(size_t)(kq + 16 * i) * N]; }
;     __syncthreads();
; #pragma unroll
;     for (int i = 0; i < 8; ++i) { tl[(kq + 16 * i) * 33 + c32] = n0a < 0 ? 0.f : va[i]; tl[128 * 33 + (kq + 16 * i) * 33 + c32] = n0b < 0 ? 0.f : vb[i]; }
;     __syncthreads();
;     const int row = tid >> 4, kc = (tid & 15) * 8;
; #pragma unroll
;     for (int h = 0; h < 2; ++h) { const float* q = tl + h * 128 * 33 + kc * 33 + row;
;       u32x4 w; w.x = cvt_pk_bf16(q[0], q[33]); w.y = cvt_pk_bf16(q[66], q[99]); w.z = cvt_pk_bf16(q[132], q[165]); w.w = cvt_pk_bf16(q[198], q[231]);
;       *(u32x4*)(dst + (size_t)(p0 + h * 32 + row) * K + k0 + kc) = w; }
	ds_read_b32 v124, v121 offset:0
	ds_read_b32 v125, v121 offset:132
	ds_read_b32 v126, v121 offset:264
	ds_read_b32 v127, v121 offset:396
	ds_read_b32 v128, v121 offset:528
	ds_read_b32 v129, v121 offset:660
	ds_read_b32 v130, v121 offset:792
	ds_read_b32 v131, v121 offset:924
	ds_read_b32 v132, v122 offset:0
	ds_read_b32 v133, v122 offset:132
	ds_read_b32 v134, v122 offset:264
	ds_read_b32 v135, v122 offset:396
	ds_read_b32 v136, v122 offset:528
	ds_read_b32 v137, v122 offset:660
	ds_read_b32 v138, v122 offset:792
	ds_read_b32 v139, v122 offset:924
	s_waitcnt lgkmcnt(8)
	v_cvt_pk_bf16_f32 v140, v124, v125
	v_cvt_pk_bf16_f32 v141, v126, v127
	v_cvt_pk_bf16_f32 v142, v128, v129
	v_cvt_pk_bf16_f32 v143, v130, v131
	global_store_dwordx4 v123, v[140:143], s[22:23]
	s_waitcnt lgkmcnt(0)
	v_cvt_pk_bf16_f32 v144, v132, v133
	v_cvt_pk_bf16_f32 v145, v134, v135
	v_cvt_pk_bf16_f32 v146, v136, v137
	v_cvt_pk_bf16_f32 v147, v138, v139
	s_add_u32 s4, s22, 0x20000
	s_addc_u32 s5, s23, 0
	global_store_dwordx4 v123, v[144:147], s[4:5]
	s_add_u32 s22, s22, 0x400000
	s_addc_u32 s23, s23, 0
	global_load_dword v80, v112, s[20:21]
	global_load_dword v88, v112, s[20:21] offset:128
	global_load_dword v81, v113, s[20:21]
	global_load_dword v89, v113, s[20:21] offset:128
	global_load_dword v82, v114, s[20:21]
	global_load_dword v90, v114, s[20:21] offset:128
	global_load_dword v83, v115, s[20:21]
	global_load_dword v91, v115, s[20:21] offset:128
	global_load_dword v84, v116, s[20:21]
	global_load_dword v92, v116, s[20:21] offset:128
	global_load_dword v85, v117, s[20:21]
	global_load_dword v93, v117, s[20:21] offset:128
	global_load_dword v86, v118, s[20:21]
	global_load_dword v94, v118, s[20:21] offset:128
	global_load_dword v87, v119, s[20:21]
	global_load_dword v95, v119, s[20:21] offset:128
	s_add_u32 s20, s20, 0x800
	s_addc_u32 s21, s21, 0
	s_waitcnt vmcnt(36)
	ds_write_b32 v120, v96 offset:33792
	ds_write_b32 v120, v104 offset:50688
	ds_write_b32 v120, v97 offset:35904
	ds_write_b32 v120, v105 offset:52800
	ds_write_b32 v120, v98 offset:38016
	ds_write_b32 v120, v106 offset:54912
	ds_write_b32 v120, v99 offset:40128
	ds_write_b32 v120, v107 offset:57024
	ds_write_b32 v120, v100 offset:42240
	ds_write_b32 v120, v108 offset:59136
	ds_write_b32 v120, v101 offset:44352
	ds_write_b32 v120, v109 offset:61248
	ds_write_b32 v120, v102 offset:46464
	ds_write_b32 v120, v110 offset:63360
	ds_write_b32 v120, v103 offset:48576
	ds_write_b32 v120, v111 offset:65472
	s_waitcnt lgkmcnt(0)
	s_barrier
	ds_read_b32 v124, v121 offset:33792
	ds_read_b32 v125, v121 offset:33924
	ds_read_b32 v126, v121 offset:34056
	ds_read_b32 v127, v121 offset:34188
	ds_read_b32 v128, v121 offset:34320
	ds_read_b32 v129, v121 offset:34452
	ds_read_b32 v130, v121 offset:34584
	ds_read_b32 v131, v121 offset:34716
	ds_read_b32 v132, v122 offset:33792
	ds_read_b32 v133, v122 offset:33924
	ds_read_b32 v134, v122 offset:34056
	ds_read_b32 v135, v122 offset:34188
	ds_read_b32 v136, v122 offset:34320
	ds_read_b32 v137, v122 offset:34452
	ds_read_b32 v138, v122 offset:34584
	ds_read_b32 v139, v122 offset:34716
	s_waitcnt lgkmcnt(8)
	v_cvt_pk_bf16_f32 v140, v124, v125
	v_cvt_pk_bf16_f32 v141, v126, v127
	v_cvt_pk_bf16_f32 v142, v128, v129
	v_cvt_pk_bf16_f32 v143, v130, v131
	global_store_dwordx4 v123, v[140:143], s[22:23]
	s_waitcnt lgkmcnt(0)
	v_cvt_pk_bf16_f32 v144, v132, v133
	v_cvt_pk_bf16_f32 v145, v134, v135
	v_cvt_pk_bf16_f32 v146, v136, v137
	v_cvt_pk_bf16_f32 v147, v138, v139
	s_add_u32 s4, s22, 0x20000
	s_addc_u32 s5, s23, 0
	global_store_dwordx4 v123, v[144:147], s[4:5]
	s_add_u32 s22, s22, 0x400000
	s_addc_u32 s23, s23, 0
	global_load_dword v96, v112, s[20:21]
	global_load_dword v104, v112, s[20:21] offset:128
	global_load_dword v97, v113, s[20:21]
	global_load_dword v105, v113, s[20:21] offset:128
	global_load_dword v98, v114, s[20:21]
	global_load_dword v106, v114, s[20:21] offset:128
	global_load_dword v99, v115, s[20:21]
	global_load_dword v107, v115, s[20:21] offset:128
	global_load_dword v100, v116, s[20:21]
	global_load_dword v108, v116, s[20:21] offset:128
	global_load_dword v101, v117, s[20:21]
	global_load_dword v109, v117, s[20:21] offset:128
	global_load_dword v102, v118, s[20:21]
	global_load_dword v110, v118, s[20:21] offset:128
	global_load_dword v103, v119, s[20:21]
	global_load_dword v111, v119, s[20:21] offset:128
	s_add_u32 s20, s20, 0x800
	s_addc_u32 s21, s21, 0
	s_waitcnt vmcnt(36)
	ds_write_b32 v120, v64 offset:0
	ds_write_b32 v120, v72 offset:16896
	ds_write_b32 v120, v65 offset:2112
	ds_write_b32 v120, v73 offset:19008
	ds_write_b32 v120, v66 offset:4224
	ds_write_b32 v120, v74 offset:21120
	ds_write_b32 v120, v67 offset:6336
	ds_write_b32 v120, v75 offset:23232
	ds_write_b32 v120, v68 offset:8448
	ds_write_b32 v120, v76 offset:25344
	ds_write_b32 v120, v69 offset:10560
	ds_write_b32 v120, v77 offset:27456
	ds_write_b32 v120, v70 offset:12672
	ds_write_b32 v120, v78 offset:29568
	ds_write_b32 v120, v71 offset:14784
	ds_write_b32 v120, v79 offset:31680
	s_waitcnt lgkmcnt(0)
	s_barrier
; __device__ __forceinline__ unsigned cvt_pk_bf16(float lo, float hi) { unsigned r; asm volatile("v_cvt_pk_bf16_f32 %0, %1, %2" : "=v"(r) : "v"(lo), "v"(hi)); return r; }
; __device__ __forceinline__ void transpose_w(const float* __restrict__ src0, const float* __restrict__ src1, int K, int N, bf16_t* __restrict__ dst, int P, int type, float* tl, int first, int stride) {
;     ...
;   for (int t = first; t < ntiles; t += stride) {
;     const int pi = t / nkt, ki = t - pi * nkt, p0 = pi * 64, k0 = ki * 128;
;     int u0, u1; const int n0a = perm_n0(type, p0, u0), n0b = perm_n0(type, p0 + 32, u1);
;     const float* sa = (u0 ? src1 : src0) + (size_t)k0 * N + (n0a < 0 ? 0 : n0a) + c32; const float* sb = (u1 ? src1 : src0) + (size_t)k0 * N + (n0b < 0 ? 0 : n0b) + c32;
;     float va[8], vb[8];
; #pragma unroll
;     for (int i = 0; i < 8; ++i) { va[i] = sa[(size_t)(kq + 16 * i) * N]; vb[i] = sb[(size_t)(kq + 16 * i) * N]; }
;     __syncthreads();
; #pragma unroll
;     for (int i = 0; i < 8; ++i) { tl[(kq + 16 * i) * 33 + c32] = n0a < 0 ? 0.f : va[i]; tl[128 * 33 + (kq + 16 * i) * 33 + c32] = n0b < 0 ? 0.f : vb[i]; }
;     __syncthreads();
;     const int row = tid >> 4, kc = (tid & 15) * 8;
; #pragma unroll
;     for (int h = 0; h < 2; ++h) { const float* q = tl + h * 128 * 33 + kc * 33 + row;
;       u32x4 w; w.x = cvt_pk_bf16(q[0], q[33]); w.y = cvt_pk_bf16(q[66], q[99]); w.z = cvt_pk_bf16(q[132], q[165]); w.w = cvt_pk_bf16(q[198], q[231]);
;       *(u32x4*)(dst + (size_t)(p0 + h * 32 + row) * K + k0 + kc) = w; }
	ds_read_b32 v124, v121 offset:0
	ds_read_b32 v125, v121 offset:132
	ds_read_b32 v126, v121 offset:264
	ds_read_b32 v127, v121 offset:396
	ds_read_b32 v128, v121 offset:528
	ds_read_b32 v129, v121 offset:660
	ds_read_b32 v130, v121 offset:792
	ds_read_b32 v131, v121 offset:924
	ds_read_b32 v132, v122 offset:0
	ds_read_b32 v133, v122 offset:132
	ds_read_b32 v134, v122 offset:264
	ds_read_b32 v135, v122 offset:396
	ds_read_b32 v136, v122 offset:528
	ds_read_b32 v137, v122 offset:660
	ds_read_b32 v138, v122 offset:792
	ds_read_b32 v139, v122 offset:924
	s_waitcnt lgkmcnt(8)
	v_cvt_pk_bf16_f32 v140, v124, v125
	v_cvt_pk_bf16_f32 v141, v126, v127
	v_cvt_pk_bf16_f32 v142, v128, v129
	v_cvt_pk_bf16_f32 v143, v130, v131
	global_store_dwordx4 v123, v[140:143], s[22:23]
	s_waitcnt lgkmcnt(0)
	v_cvt_pk_bf16_f32 v144, v132, v133
	v_cvt_pk_bf16_f32 v145, v134, v135
	v_cvt_pk_bf16_f32 v146, v136, v137
	v_cvt_pk_bf16_f32 v147, v138, v139
	s_add_u32 s4, s22, 0x20000
	s_addc_u32 s5, s23, 0
	global_store_dwordx4 v123, v[144:147], s[4:5]
	s_add_u32 s22, s22, 0x400000
	s_addc_u32 s23, s23, 0
	global_load_dword v64, v112, s[20:21]
	global_load_dword v72, v112, s[20:21] offset:128
	global_load_dword v65, v113, s[20:21]
	global_load_dword v73, v113, s[20:21] offset:128
	global_load_dword v66, v114, s[20:21]
	global_load_dword v74, v114, s[20:21] offset:128
	global_load_dword v67, v115, s[20:21]
	global_load_dword v75, v115, s[20:21] offset:128
	global_load_dword v68, v116, s[20:21]
	global_load_dword v76, v116, s[20:21] offset:128
	global_load_dword v69, v117, s[20:21]
	global_load_dword v77, v117, s[20:21] offset:128
	global_load_dword v70, v118, s[20:21]
	global_load_dword v78, v118, s[20:21] offset:128
	global_load_dword v71, v119, s[20:21]
	global_load_dword v79, v119, s[20:21] offset:128
	s_add_u32 s20, s20, 0x800
	s_addc_u32 s21, s21, 0
	s_waitcnt vmcnt(36)
	ds_write_b32 v120, v80 offset:33792
	ds_write_b32 v120, v88 offset:50688
	ds_write_b32 v120, v81 offset:35904
	ds_write_b32 v120, v89 offset:52800
	ds_write_b32 v120, v82 offset:38016
	ds_write_b32 v120, v90 offset:54912
	ds_write_b32 v120, v83 offset:40128
	ds_write_b32 v120, v91 offset:57024
	ds_write_b32 v120, v84 offset:42240
	ds_write_b32 v120, v92 offset:59136
	ds_write_b32 v120, v85 offset:44352
	ds_write_b32 v120, v93 offset:61248
	ds_write_b32 v120, v86 offset:46464
	ds_write_b32 v120, v94 offset:63360
	ds_write_b32 v120, v87 offset:48576
	ds_write_b32 v120, v95 offset:65472
	s_waitcnt lgkmcnt(0)
	s_barrier
	ds_read_b32 v124, v121 offset:33792
	ds_read_b32 v125, v121 offset:33924
	ds_read_b32 v126, v121 offset:34056
	ds_read_b32 v127, v121 offset:34188
	ds_read_b32 v128, v121 offset:34320
	ds_read_b32 v129, v121 offset:34452
	ds_read_b32 v130, v121 offset:34584
	ds_read_b32 v131, v121 offset:34716
	ds_read_b32 v132, v122 offset:33792
	ds_read_b32 v133, v122 offset:33924
	ds_read_b32 v134, v122 offset:34056
	ds_read_b32 v135, v122 offset:34188
	ds_read_b32 v136, v122 offset:34320
	ds_read_b32 v137, v122 offset:34452
	ds_read_b32 v138, v122 offset:34584
	ds_read_b32 v139, v122 offset:34716
	s_waitcnt lgkmcnt(8)
	v_cvt_pk_bf16_f32 v140, v124, v125
	v_cvt_pk_bf16_f32 v141, v126, v127
	v_cvt_pk_bf16_f32 v142, v128, v129
	v_cvt_pk_bf16_f32 v143, v130, v131
	global_store_dwordx4 v123, v[140:143], s[22:23]
	s_waitcnt lgkmcnt(0)
	v_cvt_pk_bf16_f32 v144, v132, v133
	v_cvt_pk_bf16_f32 v145, v134, v135
	v_cvt_pk_bf16_f32 v146, v136, v137
	v_cvt_pk_bf16_f32 v147, v138, v139
	s_add_u32 s4, s22, 0x20000
	s_addc_u32 s5, s23, 0
	global_store_dwordx4 v123, v[144:147], s[4:5]
	s_add_u32 s22, s22, 0x400000
	s_addc_u32 s23, s23, 0
	global_load_dword v80, v112, s[20:21]
	global_load_dword v88, v112, s[20:21] offset:128
	global_load_dword v81, v113, s[20:21]
	global_load_dword v89, v113, s[20:21] offset:128
	global_load_dword v82, v114, s[20:21]
	global_load_dword v90, v114, s[20:21] offset:128
	global_load_dword v83, v115, s[20:21]
	global_load_dword v91, v115, s[20:21] offset:128
	global_load_dword v84, v116, s[20:21]
	global_load_dword v92, v116, s[20:21] offset:128
	global_load_dword v85, v117, s[20:21]
	global_load_dword v93, v117, s[20:21] offset:128
	global_load_dword v86, v118, s[20:21]
	global_load_dword v94, v118, s[20:21] offset:128
	global_load_dword v87, v119, s[20:21]
	global_load_dword v95, v119, s[20:21] offset:128
	s_add_u32 s20, s20, 0x800
	s_addc_u32 s21, s21, 0
	s_waitcnt vmcnt(36)
	ds_write_b32 v120, v96 offset:0
	ds_write_b32 v120, v104 offset:16896
	ds_write_b32 v120, v97 offset:2112
	ds_write_b32 v120, v105 offset:19008
	ds_write_b32 v120, v98 offset:4224
	ds_write_b32 v120, v106 offset:21120
	ds_write_b32 v120, v99 offset:6336
	ds_write_b32 v120, v107 offset:23232
	ds_write_b32 v120, v100 offset:8448
	ds_write_b32 v120, v108 offset:25344
	ds_write_b32 v120, v101 offset:10560
	ds_write_b32 v120, v109 offset:27456
	ds_write_b32 v120, v102 offset:12672
	ds_write_b32 v120, v110 offset:29568
	ds_write_b32 v120, v103 offset:14784
	ds_write_b32 v120, v111 offset:31680
	s_waitcnt lgkmcnt(0)
	s_barrier
; __device__ __forceinline__ unsigned cvt_pk_bf16(float lo, float hi) { unsigned r; asm volatile("v_cvt_pk_bf16_f32 %0, %1, %2" : "=v"(r) : "v"(lo), "v"(hi)); return r; }
; __device__ __forceinline__ void transpose_w(const float* __restrict__ src0, const float* __restrict__ src1, int K, int N, bf16_t* __restrict__ dst, int P, int type, float* tl, int first, int stride) {
;     ...
;   for (int t = first; t < ntiles; t += stride) {
;     const int pi = t / nkt, ki = t - pi * nkt, p0 = pi * 64, k0 = ki * 128;
;     int u0, u1; const int n0a = perm_n0(type, p0, u0), n0b = perm_n0(type, p0 + 32, u1);
;     const float* sa = (u0 ? src1 : src0) + (size_t)k0 * N + (n0a < 0 ? 0 : n0a) + c32; const float* sb = (u1 ? src1 : src0) + (size_t)k0 * N + (n0b < 0 ? 0 : n0b) + c32;
;     float va[8], vb[8];
; #pragma unroll
;     for (int i = 0; i < 8; ++i) { va[i] = sa[(size_t)(kq + 16 * i) * N]; vb[i] = sb[(size_t)(kq + 16 * i) * N]; }
;     __syncthreads();
; #pragma unroll
;     for (int i = 0; i < 8; ++i) { tl[(kq + 16 * i) * 33 + c32] = n0a < 0 ? 0.f : va[i]; tl[128 * 33 + (kq + 16 * i) * 33 + c32] = n0b < 0 ? 0.f : vb[i]; }
;     __syncthreads();
;     const int row = tid >> 4, kc = (tid & 15) * 8;
; #pragma unroll
;     for (int h = 0; h < 2; ++h) { const float* q = tl + h * 128 * 33 + kc * 33 + row;
;       u32x4 w; w.x = cvt_pk_bf16(q[0], q[33]); w.y = cvt_pk_bf16(q[66], q[99]); w.z = cvt_pk_bf16(q[132], q[165]); w.w = cvt_pk_bf16(q[198], q[231]);
;       *(u32x4*)(dst + (size_t)(p0 + h * 32 + row) * K + k0 + kc) = w; }
	ds_read_b32 v124, v121 offset:0
	ds_read_b32 v125, v121 offset:132
	ds_read_b32 v126, v121 offset:264
	ds_read_b32 v127, v121 offset:396
	ds_read_b32 v128, v121 offset:528
	ds_read_b32 v129, v121 offset:660
	ds_read_b32 v130, v121 offset:792
	ds_read_b32 v131, v121 offset:924
	ds_read_b32 v132, v122 offset:0
	ds_read_b32 v133, v122 offset:132
	ds_read_b32 v134, v122 offset:264
	ds_read_b32 v135, v122 offset:396
	ds_read_b32 v136, v122 offset:528
	ds_read_b32 v137, v122 offset:660
	ds_read_b32 v138, v122 offset:792
	ds_read_b32 v139, v122 offset:924
	s_waitcnt lgkmcnt(8)
	v_cvt_pk_bf16_f32 v140, v124, v125
	v_cvt_pk_bf16_f32 v141, v126, v127
	v_cvt_pk_bf16_f32 v142, v128, v129
	v_cvt_pk_bf16_f32 v143, v130, v131
	global_store_dwordx4 v123, v[140:143], s[22:23]
	s_waitcnt lgkmcnt(0)
	v_cvt_pk_bf16_f32 v144, v132, v133
	v_cvt_pk_bf16_f32 v145, v134, v135
	v_cvt_pk_bf16_f32 v146, v136, v137
	v_cvt_pk_bf16_f32 v147, v138, v139
	s_add_u32 s4, s22, 0x20000
	s_addc_u32 s5, s23, 0
	global_store_dwordx4 v123, v[144:147], s[4:5]
	s_add_u32 s22, s22, 0x400000
	s_addc_u32 s23, s23, 0
	s_waitcnt vmcnt(20)
	ds_write_b32 v120, v64 offset:33792
	ds_write_b32 v120, v72 offset:50688
	ds_write_b32 v120, v65 offset:35904
	ds_write_b32 v120, v73 offset:52800
	ds_write_b32 v120, v66 offset:38016
	ds_write_b32 v120, v74 offset:54912
	ds_write_b32 v120, v67 offset:40128
	ds_write_b32 v120, v75 offset:57024
	ds_write_b32 v120, v68 offset:42240
	ds_write_b32 v120, v76 offset:59136
	ds_write_b32 v120, v69 offset:44352
	ds_write_b32 v120, v77 offset:61248
	ds_write_b32 v120, v70 offset:46464
	ds_write_b32 v120, v78 offset:63360
	ds_write_b32 v120, v71 offset:48576
	ds_write_b32 v120, v79 offset:65472
	s_waitcnt lgkmcnt(0)
	s_barrier
	ds_read_b32 v124, v121 offset:33792
	ds_read_b32 v125, v121 offset:33924
	ds_read_b32 v126, v121 offset:34056
	ds_read_b32 v127, v121 offset:34188
	ds_read_b32 v128, v121 offset:34320
	ds_read_b32 v129, v121 offset:34452
	ds_read_b32 v130, v121 offset:34584
	ds_read_b32 v131, v121 offset:34716
	ds_read_b32 v132, v122 offset:33792
	ds_read_b32 v133, v122 offset:33924
	ds_read_b32 v134, v122 offset:34056
	ds_read_b32 v135, v122 offset:34188
	ds_read_b32 v136, v122 offset:34320
	ds_read_b32 v137, v122 offset:34452
	ds_read_b32 v138, v122 offset:34584
	ds_read_b32 v139, v122 offset:34716
	s_waitcnt lgkmcnt(8)
	v_cvt_pk_bf16_f32 v140, v124, v125
	v_cvt_pk_bf16_f32 v141, v126, v127
	v_cvt_pk_bf16_f32 v142, v128, v129
	v_cvt_pk_bf16_f32 v143, v130, v131
	global_store_dwordx4 v123, v[140:143], s[22:23]
	s_waitcnt lgkmcnt(0)
	v_cvt_pk_bf16_f32 v144, v132, v133
	v_cvt_pk_bf16_f32 v145, v134, v135
	v_cvt_pk_bf16_f32 v146, v136, v137
	v_cvt_pk_bf16_f32 v147, v138, v139
	s_add_u32 s4, s22, 0x20000
	s_addc_u32 s5, s23, 0
	global_store_dwordx4 v123, v[144:147], s[4:5]
	s_add_u32 s22, s22, 0x400000
	s_addc_u32 s23, s23, 0
	s_waitcnt vmcnt(4)
	ds_write_b32 v120, v80 offset:0
	ds_write_b32 v120, v88 offset:16896
	ds_write_b32 v120, v81 offset:2112
	ds_write_b32 v120, v89 offset:19008
	ds_write_b32 v120, v82 offset:4224
	ds_write_b32 v120, v90 offset:21120
	ds_write_b32 v120, v83 offset:6336
	ds_write_b32 v120, v91 offset:23232
	ds_write_b32 v120, v84 offset:8448
	ds_write_b32 v120, v92 offset:25344
	ds_write_b32 v120, v85 offset:10560
	ds_write_b32 v120, v93 offset:27456
	ds_write_b32 v120, v86 offset:12672
	ds_write_b32 v120, v94 offset:29568
	ds_write_b32 v120, v87 offset:14784
	ds_write_b32 v120, v95 offset:31680
	s_waitcnt lgkmcnt(0)
	s_barrier
	ds_read_b32 v124, v121 offset:0
	ds_read_b32 v125, v121 offset:132
	ds_read_b32 v126, v121 offset:264
	ds_read_b32 v127, v121 offset:396
	ds_read_b32 v128, v121 offset:528
	ds_read_b32 v129, v121 offset:660
	ds_read_b32 v130, v121 offset:792
	ds_read_b32 v131, v121 offset:924
	ds_read_b32 v132, v122 offset:0
	ds_read_b32 v133, v122 offset:132
	ds_read_b32 v134, v122 offset:264
	ds_read_b32 v135, v122 offset:396
	ds_read_b32 v136, v122 offset:528
	ds_read_b32 v137, v122 offset:660
	ds_read_b32 v138, v122 offset:792
	ds_read_b32 v139, v122 offset:924
	s_waitcnt lgkmcnt(8)
	v_cvt_pk_bf16_f32 v140, v124, v125
	v_cvt_pk_bf16_f32 v141, v126, v127
	v_cvt_pk_bf16_f32 v142, v128, v129
	v_cvt_pk_bf16_f32 v143, v130, v131
	global_store_dwordx4 v123, v[140:143], s[22:23]
	s_waitcnt lgkmcnt(0)
	v_cvt_pk_bf16_f32 v144, v132, v133
	v_cvt_pk_bf16_f32 v145, v134, v135
	v_cvt_pk_bf16_f32 v146, v136, v137
	v_cvt_pk_bf16_f32 v147, v138, v139
	s_add_u32 s4, s22, 0x20000
	s_addc_u32 s5, s23, 0
	global_store_dwordx4 v123, v[144:147], s[4:5]
	s_add_u32 s22, s22, 0x400000
	s_addc_u32 s23, s23, 0
	s_branch .LBB0_76
